# k39 + seam arrive atomics (quad seams and in-epilogue quad barriers) via scalar s_atomic_add glc instead of a one-lane vector atomic
# baseline (speedup 1.0000x reference)
.LBB0_351:
	s_mov_b32 s4, 0x22170
	s_add_i32 s4, s4, 0
	v_mov_b32_e32 v0, s4
	ds_read_b32 v0, v0
	s_waitcnt lgkmcnt(0)
	v_cmp_eq_u32_e32 vcc, 0, v0
	s_cbranch_vccnz .LBB0_370
	s_mov_b64 s[16:17], s[20:21]
	s_mov_b32 s4, 0x22168
	s_add_i32 s4, s4, 0
	v_mov_b32_e32 v0, s4
	s_mov_b32 s4, 0x2216c
	ds_read_b32 v0, v0
	s_add_i32 s4, s4, 0
	s_waitcnt vmcnt(0)
	v_mov_b32_e32 v2, s4
	ds_read_b32 v2, v2
	s_waitcnt lgkmcnt(1)
	v_readfirstlane_b32 s4, v0
	s_lshl_b32 s4, s4, 10
	s_waitcnt lgkmcnt(0)
	v_readfirstlane_b32 s5, v2
	s_lshl_b32 s5, s5, 7
	s_and_b32 s5, s5, 0x380
	s_or_b32 s26, s5, s4
	s_lshl_b64 s[4:5], s[26:27], 2
	s_add_u32 s4, s16, s4
	s_addc_u32 s5, s17, s5
	s_add_u32 s6, s4, 0x10000
	s_addc_u32 s7, s5, 0
	s_mov_b32 s4, -1
	s_mov_b32 s5, s33
	v_mov_b32_e32 v2, 0
	v_mbcnt_lo_u32_b32 v0, s4, 0
	v_mbcnt_hi_u32_b32 v0, s4, v0
	v_lshl_or_b32 v0, s5, 6, v0
	s_waitcnt vmcnt(0)
	s_mov_b64 s[4:5], 0
	v_cmp_eq_u32_e32 vcc, 0, v0
	s_barrier
	s_and_saveexec_b64 s[22:23], vcc
	s_cbranch_execz .LBB0_356
	s_mov_b64 s[24:25], exec
	v_mbcnt_lo_u32_b32 v0, s24, 0
	v_mbcnt_hi_u32_b32 v0, s25, v0
	v_cmp_eq_u32_e64 s[4:5], 0, v0
	s_waitcnt vmcnt(0) expcnt(0) lgkmcnt(0)
	s_and_saveexec_b64 s[40:41], s[4:5]
	s_cbranch_execz .LBB0_355
	s_bcnt1_i32_b64 s4, s[24:25]
	s_mov_b32 s100, s4
	s_atomic_add s100, s[6:7], 0x0 glc
.LBB0_355:
	s_or_b64 exec, exec, s[40:41]
	s_waitcnt lgkmcnt(0)
	s_mov_b32 s4, s100
	s_nop 0
	v_add_u32_e32 v0, s4, v0
	v_and_b32_e32 v2, -4, v0
	v_and_b32_e32 v0, 3, v0
	v_cmp_eq_u32_e64 s[4:5], 3, v0
	v_add_u32_e32 v2, 4, v2
	s_and_b64 s[4:5], s[4:5], exec

.LBB0_640:
	s_nop 0
	v_readlane_b32 s2, v255, 10
	v_readlane_b32 s3, v255, 11
	s_and_b64 s[22:23], s[2:3], s[8:9]
	s_xor_b64 s[16:17], s[22:23], -1
	s_mov_b64 s[2:3], -1
	s_and_b64 vcc, exec, s[16:17]
	s_cbranch_vccz .LBB0_733
	s_mov_b32 s2, 0x22170
	s_add_i32 s2, s2, 0
	v_mov_b32_e32 v0, s2
	ds_read_b32 v0, v0
	s_waitcnt lgkmcnt(0)
	v_cmp_eq_u32_e32 vcc, 0, v0
	s_cbranch_vccnz .LBB0_670
	s_mov_b64 s[48:49], s[20:21]
	s_mov_b32 s2, 0x22168
	s_add_i32 s2, s2, 0
	v_mov_b32_e32 v0, s2
	s_mov_b32 s2, 0x2216c
	ds_read_b32 v0, v0
	s_add_i32 s2, s2, 0
	s_waitcnt vmcnt(0)
	v_mov_b32_e32 v2, s2
	ds_read_b32 v2, v2
	s_waitcnt lgkmcnt(1)
	v_readfirstlane_b32 s2, v0
	s_lshl_b32 s2, s2, 10
	s_waitcnt lgkmcnt(0)
	v_readfirstlane_b32 s3, v2
	s_lshl_b32 s3, s3, 7
	s_and_b32 s3, s3, 0x380
	s_or_b32 s26, s3, s2
	s_lshl_b64 s[2:3], s[26:27], 2
	s_add_u32 s2, s48, s2
	s_addc_u32 s3, s49, s3
	s_add_u32 s46, s2, 0x10000
	s_addc_u32 s47, s3, 0
	s_mov_b32 s2, s33
	s_mov_b32 s3, -1
	v_mov_b32_e32 v2, 0
	v_mbcnt_lo_u32_b32 v0, s3, 0
	v_mbcnt_hi_u32_b32 v0, s3, v0
	v_lshl_or_b32 v0, s2, 6, v0
	s_waitcnt vmcnt(0)
	s_mov_b64 s[2:3], 0
	v_cmp_eq_u32_e32 vcc, 0, v0
	s_barrier
	s_and_saveexec_b64 s[24:25], vcc
	s_cbranch_execz .LBB0_646
	s_mov_b64 s[40:41], exec
	v_mbcnt_lo_u32_b32 v0, s40, 0
	v_mbcnt_hi_u32_b32 v0, s41, v0
	v_cmp_eq_u32_e64 s[2:3], 0, v0
	s_waitcnt vmcnt(0) expcnt(0) lgkmcnt(0)
	s_and_saveexec_b64 s[42:43], s[2:3]
	s_cbranch_execz .LBB0_645
	s_bcnt1_i32_b64 s2, s[40:41]
	s_mov_b32 s100, s2
	s_atomic_add s100, s[46:47], 0x0 glc
.LBB0_645:
	s_or_b64 exec, exec, s[42:43]
	s_waitcnt lgkmcnt(0)
	s_mov_b32 s2, s100
	s_nop 0
	v_add_u32_e32 v0, s2, v0
	v_and_b32_e32 v2, -4, v0
	v_and_b32_e32 v0, 3, v0
	v_cmp_eq_u32_e64 s[2:3], 3, v0
	v_add_u32_e32 v2, 4, v2
	s_and_b64 s[2:3], s[2:3], exec

.LBB0_733:
	s_andn2_b64 vcc, exec, s[2:3]
	s_cbranch_vccnz .LBB0_815
	s_mov_b32 s2, 0x22170
	s_add_i32 s2, s2, 0
	v_mov_b32_e32 v0, s2
	ds_read_b32 v0, v0
	s_waitcnt lgkmcnt(0)
	v_cmp_eq_u32_e32 vcc, 0, v0
	s_cbranch_vccnz .LBB0_753
	s_mov_b64 s[48:49], s[20:21]
	s_mov_b32 s2, 0x22168
	s_add_i32 s2, s2, 0
	v_mov_b32_e32 v0, s2
	ds_read_b32 v0, v0
	s_mov_b32 s4, s33
	s_mov_b32 s5, -1
	s_waitcnt vmcnt(0)
	v_mov_b32_e32 v2, 0
	s_waitcnt lgkmcnt(0)
	v_readfirstlane_b32 s2, v0
	s_lshl_b32 s26, s2, 6
	v_mbcnt_lo_u32_b32 v0, s5, 0
	s_lshl_b64 s[2:3], s[26:27], 2
	v_mbcnt_hi_u32_b32 v0, s5, v0
	s_add_u32 s2, s48, s2
	v_lshl_or_b32 v0, s4, 6, v0
	s_addc_u32 s3, s49, s3
	s_waitcnt vmcnt(0)
	s_add_u32 s46, s2, 0x18000
	s_addc_u32 s47, s3, 0
	v_cmp_eq_u32_e32 vcc, 0, v0
	s_mov_b64 s[2:3], 0
	s_barrier
	s_and_saveexec_b64 s[24:25], vcc
	s_cbranch_execz .LBB0_739
	s_mov_b64 s[40:41], exec
	v_mbcnt_lo_u32_b32 v0, s40, 0
	v_mbcnt_hi_u32_b32 v0, s41, v0
	v_cmp_eq_u32_e64 s[2:3], 0, v0
	s_waitcnt vmcnt(0) expcnt(0) lgkmcnt(0)
	s_and_saveexec_b64 s[42:43], s[2:3]
	s_cbranch_execz .LBB0_738
	s_bcnt1_i32_b64 s2, s[40:41]
	s_mov_b32 s100, s2
	s_atomic_add s100, s[46:47], 0x0 glc
.LBB0_738:
	s_or_b64 exec, exec, s[42:43]
	s_waitcnt lgkmcnt(0)
	s_mov_b32 s2, s100
	s_nop 0
	v_add_u32_e32 v0, s2, v0
	v_and_b32_e32 v2, 0xffffffe0, v0
	v_and_b32_e32 v0, 31, v0
	v_cmp_eq_u32_e64 s[2:3], 31, v0
	v_add_u32_e32 v2, 32, v2
	s_and_b64 s[2:3], s[2:3], exec

.LBB0_840:
	s_or_b64 exec, exec, s[24:25]
	s_or_b32 s4, s41, s40
	s_waitcnt vmcnt(0)
	s_barrier
	v_or3_b32 v0, s4, v196, v197
	v_cmp_eq_u32_e32 vcc, 0, v0
	s_and_saveexec_b64 s[46:47], vcc
	s_cbranch_execz .LBB0_859
	s_lshl_b32 s5, s43, 7
	s_lshl_b32 s4, s42, 10
	s_and_b32 s5, s5, 0x380
	s_or_b32 s26, s5, s4
	s_lshl_b64 s[4:5], s[26:27], 2
	s_mov_b64 s[40:41], exec
	s_add_u32 s4, s22, s4
	s_addc_u32 s5, s23, s5
	v_mbcnt_lo_u32_b32 v0, s40, 0
	s_add_u32 s24, s4, 0x10000
	v_mbcnt_hi_u32_b32 v0, s41, v0
	s_addc_u32 s25, s5, 0
	v_cmp_eq_u32_e32 vcc, 0, v0
	s_waitcnt vmcnt(0) expcnt(0) lgkmcnt(0)
	s_and_saveexec_b64 s[42:43], vcc
	s_cbranch_execz .LBB0_843
	s_bcnt1_i32_b64 s4, s[40:41]
	s_mov_b32 s100, s4
	s_atomic_add s100, s[24:25], 0x0 glc
.LBB0_843:
	s_or_b64 exec, exec, s[42:43]
	s_waitcnt lgkmcnt(0)
	s_mov_b32 s4, s100
	s_nop 0
	v_add_u32_e32 v0, s4, v0
	v_and_b32_e32 v2, 3, v0
	v_cmp_ne_u32_e32 vcc, 3, v2
	s_and_saveexec_b64 s[40:41], vcc
	s_cbranch_execz .LBB0_858
	global_load_dword v2, v1, s[24:25] sc1
	v_bitop3_b32 v0, v0, -4, v0 bitop3:0xc
	s_waitcnt vmcnt(0)
	v_add_u32_e32 v2, v2, v0
	v_cmp_gt_i32_e32 vcc, 0, v2
	s_and_b64 exec, exec, vcc
	s_cbranch_execz .LBB0_858
	s_add_u32 s22, s22, 0x4200
	s_addc_u32 s23, s23, 0
	s_mov_b32 s4, 1
	s_mov_b64 s[42:43], 0
	s_branch .LBB0_847

.LBB0_888:
	s_or_b64 exec, exec, s[22:23]
	s_or_b32 s4, s61, s40
	s_waitcnt vmcnt(0)
	s_barrier
	v_or3_b32 v0, s4, v159, v158
	v_cmp_eq_u32_e32 vcc, 0, v0
	s_and_saveexec_b64 s[22:23], vcc
	s_cbranch_execz .LBB0_907
	s_lshl_b32 s5, s43, 7
	s_lshl_b32 s4, s42, 10
	s_and_b32 s5, s5, 0x380
	s_or_b32 s26, s5, s4
	s_lshl_b64 s[4:5], s[26:27], 2
	s_mov_b64 s[40:41], exec
	s_add_u32 s4, s6, s4
	s_addc_u32 s5, s7, s5
	v_mbcnt_lo_u32_b32 v0, s40, 0
	s_add_u32 s24, s4, 0x10000
	v_mbcnt_hi_u32_b32 v0, s41, v0
	s_addc_u32 s25, s5, 0
	v_cmp_eq_u32_e32 vcc, 0, v0
	s_waitcnt vmcnt(0) expcnt(0) lgkmcnt(0)
	s_and_saveexec_b64 s[42:43], vcc
	s_cbranch_execz .LBB0_891
	s_bcnt1_i32_b64 s4, s[40:41]
	s_mov_b32 s100, s4
	s_atomic_add s100, s[24:25], 0x0 glc
.LBB0_891:
	s_or_b64 exec, exec, s[42:43]
	s_waitcnt lgkmcnt(0)
	s_mov_b32 s4, s100
	s_nop 0
	v_add_u32_e32 v0, s4, v0
	v_and_b32_e32 v2, 3, v0
	v_cmp_ne_u32_e32 vcc, 3, v2
	s_and_saveexec_b64 s[40:41], vcc
	s_cbranch_execz .LBB0_906
	global_load_dword v2, v1, s[24:25] sc1
	v_bitop3_b32 v0, v0, -4, v0 bitop3:0xc
	s_waitcnt vmcnt(0)
	v_add_u32_e32 v2, v2, v0
	v_cmp_gt_i32_e32 vcc, 0, v2
	s_and_b64 exec, exec, vcc
	s_cbranch_execz .LBB0_906
	s_add_u32 s6, s6, 0x4200
	s_addc_u32 s7, s7, 0
	s_mov_b32 s4, 1
	s_mov_b64 s[42:43], 0
	s_branch .LBB0_895

.LBB0_994:
	s_mov_b32 s2, 0x22170
	s_add_i32 s2, s2, 0
	v_mov_b32_e32 v0, s2
	ds_read_b32 v0, v0
	s_waitcnt lgkmcnt(0)
	v_cmp_eq_u32_e32 vcc, 0, v0
	s_cbranch_vccnz .LBB0_1014
	s_mov_b64 s[10:11], s[20:21]
	s_mov_b32 s2, 0x22168
	s_add_i32 s2, s2, 0
	v_mov_b32_e32 v0, s2
	s_mov_b32 s2, 0x2216c
	ds_read_b32 v0, v0
	s_add_i32 s2, s2, 0
	s_waitcnt vmcnt(0)
	v_mov_b32_e32 v2, s2
	ds_read_b32 v2, v2
	s_waitcnt lgkmcnt(1)
	v_readfirstlane_b32 s2, v0
	s_lshl_b32 s2, s2, 10
	s_waitcnt lgkmcnt(0)
	v_readfirstlane_b32 s3, v2
	s_lshl_b32 s3, s3, 7
	s_and_b32 s3, s3, 0x380
	s_or_b32 s26, s3, s2
	s_lshl_b64 s[2:3], s[26:27], 2
	s_add_u32 s2, s10, s2
	s_addc_u32 s3, s11, s3
	s_add_u32 s8, s2, 0x10000
	s_addc_u32 s9, s3, 0
	s_mov_b32 s2, s33
	s_mov_b32 s3, -1
	v_mov_b32_e32 v2, 0
	v_mbcnt_lo_u32_b32 v0, s3, 0
	v_mbcnt_hi_u32_b32 v0, s3, v0
	v_lshl_or_b32 v0, s2, 6, v0
	s_waitcnt vmcnt(0)
	s_mov_b64 s[2:3], 0
	v_cmp_eq_u32_e32 vcc, 0, v0
	s_barrier
	s_and_saveexec_b64 s[12:13], vcc
	s_cbranch_execz .LBB0_999
	s_mov_b64 s[14:15], exec
	v_mbcnt_lo_u32_b32 v0, s14, 0
	v_mbcnt_hi_u32_b32 v0, s15, v0
	v_cmp_eq_u32_e64 s[2:3], 0, v0
	s_waitcnt vmcnt(0) expcnt(0) lgkmcnt(0)
	s_and_saveexec_b64 s[16:17], s[2:3]
	s_cbranch_execz .LBB0_998
	s_bcnt1_i32_b64 s2, s[14:15]
	s_mov_b32 s100, s2
	s_atomic_add s100, s[8:9], 0x0 glc
.LBB0_998:
	s_or_b64 exec, exec, s[16:17]
	s_waitcnt lgkmcnt(0)
	s_mov_b32 s2, s100
	s_nop 0
	v_add_u32_e32 v0, s2, v0
	v_and_b32_e32 v2, -4, v0
	v_and_b32_e32 v0, 3, v0
	v_cmp_eq_u32_e64 s[2:3], 3, v0
	v_add_u32_e32 v2, 4, v2
	s_and_b64 s[2:3], s[2:3], exec

.LBB0_1219:
	s_mov_b32 s2, 0x22170
	s_add_i32 s2, s2, 0
	s_waitcnt vmcnt(0)
	v_mov_b32_e32 v0, s2
	ds_read_b32 v0, v0
	s_waitcnt lgkmcnt(0)
	v_cmp_eq_u32_e32 vcc, 0, v0
	s_cbranch_vccnz .LBB0_1233
	s_mov_b64 s[8:9], s[20:21]
	s_mov_b32 s2, 0x22168
	s_add_i32 s2, s2, 0
	v_mov_b32_e32 v0, s2
	ds_read_b32 v0, v0
	s_mov_b32 s2, s33
	s_mov_b32 s3, -1
	s_waitcnt lgkmcnt(0)
	v_readfirstlane_b32 s4, v0
	v_mbcnt_lo_u32_b32 v0, s3, 0
	v_mbcnt_hi_u32_b32 v0, s3, v0
	v_lshl_or_b32 v0, s2, 6, v0
	s_waitcnt vmcnt(0)
	s_nop 0
	v_cmp_eq_u32_e32 vcc, 0, v0
	s_barrier
	s_and_saveexec_b64 s[2:3], vcc
	s_cbranch_execz .LBB0_1238
	s_lshl_b32 s26, s4, 6
	s_lshl_b64 s[4:5], s[26:27], 2
	s_mov_b64 s[6:7], exec
	s_add_u32 s4, s8, s4
	s_addc_u32 s5, s9, s5
	v_mbcnt_lo_u32_b32 v0, s6, 0
	s_add_u32 s4, s4, 0x18000
	v_mbcnt_hi_u32_b32 v0, s7, v0
	s_addc_u32 s5, s5, 0
	v_cmp_eq_u32_e32 vcc, 0, v0
	s_waitcnt vmcnt(0) expcnt(0) lgkmcnt(0)
	s_and_saveexec_b64 s[10:11], vcc
	s_cbranch_execz .LBB0_1223
	s_bcnt1_i32_b64 s6, s[6:7]
	s_mov_b32 s100, s6
	s_atomic_add s100, s[4:5], 0x0 glc
.LBB0_1223:
	s_or_b64 exec, exec, s[10:11]
	s_waitcnt lgkmcnt(0)
	s_mov_b32 s6, s100
	s_nop 0
	v_add_u32_e32 v0, s6, v0
	v_and_b32_e32 v2, 31, v0
	v_cmp_ne_u32_e32 vcc, 31, v2
	s_and_saveexec_b64 s[6:7], vcc
	s_cbranch_execz .LBB0_1237
	global_load_dword v2, v1, s[4:5] sc1
	s_movk_i32 s10, 0xffe0
	v_bitop3_b32 v0, v0, s10, v0 bitop3:0xc
	s_waitcnt vmcnt(0)
	v_add_u32_e32 v2, v2, v0
	v_cmp_gt_i32_e32 vcc, 0, v2
	s_and_b64 exec, exec, vcc
	s_cbranch_execz .LBB0_1237
	s_add_u32 s8, s8, 0x4200
	s_addc_u32 s9, s9, 0
	s_mov_b32 s24, 1
	s_mov_b64 s[10:11], 0
	s_branch .LBB0_1227

.LBB0_1485:
	s_mov_b64 s[4:5], s[20:21]
	v_readlane_b32 s2, v255, 16
	s_mov_b32 s6, 0x22174
	s_add_u32 s2, s4, s2
	s_addc_u32 s3, s5, 0
	s_add_i32 s6, s6, 0
	v_mov_b32_e32 v0, s6
	ds_read_b32 v0, v0
	s_add_u32 s37, s2, 0x1280000
	s_addc_u32 s64, s3, 0
	s_waitcnt lgkmcnt(0)
	v_readfirstlane_b32 s65, v0
	s_cmpk_lt_u32 s65, 0x100
	s_cselect_b64 s[6:7], -1, 0
	s_lshl_b32 s2, s65, 13
	s_and_b32 s2, s2, 0x180000
	s_add_u32 s8, s37, s2
	s_addc_u32 s9, s64, 0
	s_and_b64 s[2:3], s[6:7], exec
	v_readlane_b32 s2, v255, 34
	v_readlane_b32 s3, v255, 35
	s_cselect_b32 s3, s9, s3
	s_cselect_b32 s2, s8, s2
	v_writelane_b32 v255, s2, 34
	s_nop 1
	v_writelane_b32 v255, s3, 35
	s_mov_b32 s2, 0x22170
	s_add_i32 s2, s2, 0
	v_mov_b32_e32 v0, s2
	ds_read_b32 v0, v0
	s_waitcnt lgkmcnt(0)
	v_cmp_eq_u32_e32 vcc, 0, v0
	s_cbranch_vccnz .LBB0_1504
	s_mov_b64 s[10:11], s[20:21]
	s_mov_b32 s2, 0x22168
	s_add_i32 s2, s2, 0
	v_mov_b32_e32 v0, s2
	ds_read_b32 v0, v0
	s_mov_b32 s12, s33
	s_mov_b32 s13, -1
	v_mov_b32_e32 v2, 0
	s_waitcnt lgkmcnt(0)
	v_readfirstlane_b32 s2, v0
	s_lshl_b32 s26, s2, 6
	v_mbcnt_lo_u32_b32 v0, s13, 0
	s_lshl_b64 s[2:3], s[26:27], 2
	v_mbcnt_hi_u32_b32 v0, s13, v0
	s_add_u32 s2, s10, s2
	v_lshl_or_b32 v0, s12, 6, v0
	s_addc_u32 s3, s11, s3
	s_waitcnt vmcnt(0)
	s_add_u32 s8, s2, 0x18000
	s_addc_u32 s9, s3, 0
	v_cmp_eq_u32_e32 vcc, 0, v0
	s_mov_b64 s[2:3], 0
	s_waitcnt vmcnt(0)
	s_barrier
	s_and_saveexec_b64 s[12:13], vcc
	s_cbranch_execz .LBB0_1490
	s_mov_b64 s[14:15], exec
	v_mbcnt_lo_u32_b32 v0, s14, 0
	v_mbcnt_hi_u32_b32 v0, s15, v0
	v_cmp_eq_u32_e64 s[2:3], 0, v0
	s_waitcnt vmcnt(0) expcnt(0) lgkmcnt(0)
	s_and_saveexec_b64 s[16:17], s[2:3]
	s_cbranch_execz .LBB0_1489
	s_bcnt1_i32_b64 s2, s[14:15]
	s_mov_b32 s100, s2
	s_atomic_add s100, s[8:9], 0x0 glc
.LBB0_1489:
	s_or_b64 exec, exec, s[16:17]
	s_waitcnt lgkmcnt(0)
	s_mov_b32 s2, s100
	s_nop 0
	v_add_u32_e32 v0, s2, v0
	v_and_b32_e32 v2, 0xffffffe0, v0
	v_and_b32_e32 v0, 31, v0
	v_cmp_eq_u32_e64 s[2:3], 31, v0
	v_add_u32_e32 v2, 32, v2
	s_and_b64 s[2:3], s[2:3], exec

.LBB0_1594:
	s_mov_b32 s2, 0x22170
	s_add_i32 s2, s2, 0
	v_mov_b32_e32 v0, s2
	ds_read_b32 v0, v0
	s_waitcnt lgkmcnt(0)
	v_cmp_eq_u32_e32 vcc, 0, v0
	s_cbranch_vccnz .LBB0_1613
	s_mov_b64 s[10:11], s[20:21]
	s_mov_b32 s2, 0x22168
	s_add_i32 s2, s2, 0
	v_mov_b32_e32 v0, s2
	s_mov_b32 s2, 0x2216c
	ds_read_b32 v0, v0
	s_add_i32 s2, s2, 0
	v_mov_b32_e32 v2, s2
	ds_read_b32 v2, v2
	s_waitcnt lgkmcnt(0)
	v_readfirstlane_b32 s2, v0
	s_lshl_b32 s2, s2, 10
	v_readfirstlane_b32 s3, v2
	s_lshl_b32 s3, s3, 7
	s_and_b32 s3, s3, 0x380
	s_or_b32 s26, s3, s2
	s_lshl_b64 s[2:3], s[26:27], 2
	s_add_u32 s2, s10, s2
	s_addc_u32 s3, s11, s3
	s_add_u32 s8, s2, 0x10000
	s_addc_u32 s9, s3, 0
	s_mov_b32 s2, s33
	s_mov_b32 s3, -1
	v_mov_b32_e32 v2, 0
	v_mbcnt_lo_u32_b32 v0, s3, 0
	v_mbcnt_hi_u32_b32 v0, s3, v0
	v_lshl_or_b32 v0, s2, 6, v0
	s_waitcnt vmcnt(0)
	s_mov_b64 s[2:3], 0
	v_cmp_eq_u32_e32 vcc, 0, v0
	s_waitcnt vmcnt(0)
	s_barrier
	s_and_saveexec_b64 s[12:13], vcc
	s_cbranch_execz .LBB0_1599
	s_mov_b64 s[14:15], exec
	v_mbcnt_lo_u32_b32 v0, s14, 0
	v_mbcnt_hi_u32_b32 v0, s15, v0
	v_cmp_eq_u32_e64 s[2:3], 0, v0
	s_waitcnt vmcnt(0) expcnt(0) lgkmcnt(0)
	s_and_saveexec_b64 s[16:17], s[2:3]
	s_cbranch_execz .LBB0_1598
	s_bcnt1_i32_b64 s2, s[14:15]
	s_mov_b32 s100, s2
	s_atomic_add s100, s[8:9], 0x0 glc

.LBB0_1719:
	s_mov_b32 s2, 0x22170
	s_add_i32 s2, s2, 0
	v_mov_b32_e32 v0, s2
	ds_read_b32 v0, v0
	s_waitcnt lgkmcnt(0)
	v_cmp_eq_u32_e32 vcc, 0, v0
	s_cbranch_vccnz .LBB0_1738
	s_mov_b64 s[12:13], s[20:21]
	s_mov_b32 s2, 0x22168
	s_add_i32 s2, s2, 0
	v_mov_b32_e32 v0, s2
	s_mov_b32 s2, 0x2216c
	ds_read_b32 v0, v0
	s_add_i32 s2, s2, 0
	v_mov_b32_e32 v2, s2
	ds_read_b32 v2, v2
	s_waitcnt lgkmcnt(0)
	v_readfirstlane_b32 s2, v0
	s_lshl_b32 s2, s2, 10
	v_readfirstlane_b32 s3, v2
	s_lshl_b32 s3, s3, 7
	s_and_b32 s3, s3, 0x380
	s_or_b32 s26, s3, s2
	s_lshl_b64 s[2:3], s[26:27], 2
	s_add_u32 s2, s12, s2
	s_addc_u32 s3, s13, s3
	s_add_u32 s6, s2, 0x10000
	s_addc_u32 s7, s3, 0
	s_mov_b32 s2, s33
	s_mov_b32 s3, -1
	v_mov_b32_e32 v2, 0
	v_mbcnt_lo_u32_b32 v0, s3, 0
	v_mbcnt_hi_u32_b32 v0, s3, v0
	v_lshl_or_b32 v0, s2, 6, v0
	s_waitcnt vmcnt(0)
	s_mov_b64 s[2:3], 0
	v_cmp_eq_u32_e32 vcc, 0, v0
	s_waitcnt vmcnt(0)
	s_barrier
	s_and_saveexec_b64 s[14:15], vcc
	s_cbranch_execz .LBB0_1724
	s_mov_b64 s[16:17], exec
	v_mbcnt_lo_u32_b32 v0, s16, 0
	v_mbcnt_hi_u32_b32 v0, s17, v0
	v_cmp_eq_u32_e64 s[2:3], 0, v0
	s_waitcnt vmcnt(0) expcnt(0) lgkmcnt(0)
	s_and_saveexec_b64 s[22:23], s[2:3]
	s_cbranch_execz .LBB0_1723
	s_bcnt1_i32_b64 s2, s[16:17]
	s_mov_b32 s100, s2
	s_atomic_add s100, s[6:7], 0x0 glc
.LBB0_1723:
	s_or_b64 exec, exec, s[22:23]
	s_waitcnt lgkmcnt(0)
	s_mov_b32 s2, s100
	s_nop 0
	v_add_u32_e32 v0, s2, v0
	v_and_b32_e32 v2, -4, v0
	v_and_b32_e32 v0, 3, v0
	v_cmp_eq_u32_e64 s[2:3], 3, v0
	v_add_u32_e32 v2, 4, v2
	s_and_b64 s[2:3], s[2:3], exec

.LBB0_1826:
	s_or_b64 exec, exec, s[16:17]
	s_or_b32 s16, s61, s24
	s_waitcnt vmcnt(0)
	s_barrier
	v_or3_b32 v0, s16, v159, v158
	v_cmp_eq_u32_e32 vcc, 0, v0
	s_and_saveexec_b64 s[16:17], vcc
	s_cbranch_execz .LBB0_1844
	s_lshl_b32 s23, s41, 7
	s_lshl_b32 s22, s40, 10
	s_and_b32 s23, s23, 0x380
	s_or_b32 s26, s23, s22
	s_lshl_b64 s[22:23], s[26:27], 2
	s_mov_b64 s[24:25], exec
	s_add_u32 s22, s6, s22
	s_addc_u32 s23, s7, s23
	v_mbcnt_lo_u32_b32 v0, s24, 0
	s_add_u32 s22, s22, 0x10000
	v_mbcnt_hi_u32_b32 v0, s25, v0
	s_addc_u32 s23, s23, 0
	v_cmp_eq_u32_e32 vcc, 0, v0
	s_waitcnt vmcnt(0) expcnt(0) lgkmcnt(0)
	s_and_saveexec_b64 s[40:41], vcc
	s_cbranch_execz .LBB0_1829
	s_bcnt1_i32_b64 s24, s[24:25]
	s_mov_b32 s100, s24
	s_atomic_add s100, s[22:23], 0x0 glc
.LBB0_1829:
	s_or_b64 exec, exec, s[40:41]
	s_waitcnt lgkmcnt(0)
	s_mov_b32 s24, s100
	s_nop 0
	v_add_u32_e32 v0, s24, v0
	v_and_b32_e32 v2, 3, v0
	v_cmp_ne_u32_e32 vcc, 3, v2
	s_and_saveexec_b64 s[24:25], vcc
	s_cbranch_execz .LBB0_1843
	global_load_dword v2, v1, s[22:23] sc1
	v_bitop3_b32 v0, v0, -4, v0 bitop3:0xc
	s_waitcnt vmcnt(0)
	v_add_u32_e32 v2, v2, v0
	v_cmp_gt_i32_e32 vcc, 0, v2
	s_and_b64 exec, exec, vcc
	s_cbranch_execz .LBB0_1843
	s_add_u32 s6, s6, 0x4200
	s_addc_u32 s7, s7, 0
	s_mov_b32 s26, 1
	s_mov_b64 s[40:41], 0
	s_branch .LBB0_1833

.LBB0_1906:
	s_mov_b32 s2, 0x22170
	s_add_i32 s2, s2, 0
	v_mov_b32_e32 v0, s2
	ds_read_b32 v0, v0
	s_movk_i32 s76, 0x7f
	s_waitcnt lgkmcnt(0)
	v_cmp_ne_u32_e32 vcc, 0, v0
	s_cbranch_vccnz .LBB0_1980
	s_mov_b32 s2, 0x22170
	s_add_i32 s2, s2, 0
	v_mov_b32_e32 v0, s2
	ds_read_b32 v0, v0
	s_waitcnt lgkmcnt(0)
	v_cmp_eq_u32_e32 vcc, 0, v0
	s_cbranch_vccnz .LBB0_1921
	s_mov_b64 s[8:9], s[20:21]
	s_mov_b32 s2, 0x22168
	s_add_i32 s2, s2, 0
	v_mov_b32_e32 v0, s2
	ds_read_b32 v0, v0
	s_mov_b32 s2, 0x2216c
	s_add_i32 s2, s2, 0
	s_mov_b32 s3, -1
	s_waitcnt lgkmcnt(0)
	v_readfirstlane_b32 s4, v0
	v_mov_b32_e32 v0, s2
	ds_read_b32 v0, v0
	s_mov_b32 s2, s33
	s_waitcnt lgkmcnt(0)
	v_readfirstlane_b32 s5, v0
	v_mbcnt_lo_u32_b32 v0, s3, 0
	v_mbcnt_hi_u32_b32 v0, s3, v0
	v_lshl_or_b32 v0, s2, 6, v0
	s_waitcnt vmcnt(0)
	s_waitcnt vmcnt(0)
	v_cmp_eq_u32_e32 vcc, 0, v0
	s_barrier
	s_and_saveexec_b64 s[2:3], vcc
	s_cbranch_execz .LBB0_1926
	s_lshl_b32 s5, s5, 7
	s_lshl_b32 s4, s4, 10
	s_and_b32 s5, s5, 0x380
	s_or_b32 s26, s5, s4
	s_lshl_b64 s[4:5], s[26:27], 2
	s_mov_b64 s[6:7], exec
	s_add_u32 s4, s8, s4
	s_addc_u32 s5, s9, s5
	v_mbcnt_lo_u32_b32 v0, s6, 0
	s_add_u32 s4, s4, 0x10000
	v_mbcnt_hi_u32_b32 v0, s7, v0
	s_addc_u32 s5, s5, 0
	v_cmp_eq_u32_e32 vcc, 0, v0
	s_waitcnt vmcnt(0) expcnt(0) lgkmcnt(0)
	s_and_saveexec_b64 s[10:11], vcc
	s_cbranch_execz .LBB0_1911
	s_bcnt1_i32_b64 s6, s[6:7]
	s_mov_b32 s100, s6
	s_atomic_add s100, s[4:5], 0x0 glc
.LBB0_1911:
	s_or_b64 exec, exec, s[10:11]
	s_waitcnt lgkmcnt(0)
	s_mov_b32 s6, s100
	s_nop 0
	v_add_u32_e32 v0, s6, v0
	v_and_b32_e32 v2, 3, v0
	v_cmp_ne_u32_e32 vcc, 3, v2
	s_and_saveexec_b64 s[6:7], vcc
	s_cbranch_execz .LBB0_1925
	global_load_dword v2, v1, s[4:5] sc1
	v_bitop3_b32 v0, v0, -4, v0 bitop3:0xc
	s_waitcnt vmcnt(0)
	v_add_u32_e32 v2, v2, v0
	v_cmp_gt_i32_e32 vcc, 0, v2
	s_and_b64 exec, exec, vcc
	s_cbranch_execz .LBB0_1925
	s_add_u32 s8, s8, 0x4200
	s_addc_u32 s9, s9, 0
	s_mov_b32 s24, 1
	s_mov_b64 s[10:11], 0
	s_branch .LBB0_1915

.LBB0_1984:
	s_mov_b32 s2, 0x22170
	s_add_i32 s2, s2, 0
	v_mov_b32_e32 v0, s2
	ds_read_b32 v0, v0
	s_waitcnt lgkmcnt(0)
	v_cmp_eq_u32_e32 vcc, 0, v0
	s_cbranch_vccnz .LBB0_1998
	s_mov_b64 s[8:9], s[20:21]
	s_mov_b32 s2, 0x22168
	s_add_i32 s2, s2, 0
	v_mov_b32_e32 v0, s2
	ds_read_b32 v0, v0
	s_mov_b32 s2, 0x2216c
	s_add_i32 s2, s2, 0
	s_mov_b32 s3, -1
	s_waitcnt lgkmcnt(0)
	v_readfirstlane_b32 s4, v0
	v_mov_b32_e32 v0, s2
	ds_read_b32 v0, v0
	s_mov_b32 s2, s33
	s_waitcnt lgkmcnt(0)
	v_readfirstlane_b32 s5, v0
	v_mbcnt_lo_u32_b32 v0, s3, 0
	v_mbcnt_hi_u32_b32 v0, s3, v0
	v_lshl_or_b32 v0, s2, 6, v0
	s_waitcnt vmcnt(0)
	s_waitcnt vmcnt(0)
	v_cmp_eq_u32_e32 vcc, 0, v0
	s_barrier
	s_and_saveexec_b64 s[2:3], vcc
	s_cbranch_execz .LBB0_2003
	s_lshl_b32 s5, s5, 7
	s_lshl_b32 s4, s4, 10
	s_and_b32 s5, s5, 0x380
	s_or_b32 s26, s5, s4
	s_lshl_b64 s[4:5], s[26:27], 2
	s_mov_b64 s[6:7], exec
	s_add_u32 s4, s8, s4
	s_addc_u32 s5, s9, s5
	v_mbcnt_lo_u32_b32 v0, s6, 0
	s_add_u32 s4, s4, 0x10000
	v_mbcnt_hi_u32_b32 v0, s7, v0
	s_addc_u32 s5, s5, 0
	v_cmp_eq_u32_e32 vcc, 0, v0
	s_waitcnt vmcnt(0) expcnt(0) lgkmcnt(0)
	s_and_saveexec_b64 s[10:11], vcc
	s_cbranch_execz .LBB0_1988
	s_bcnt1_i32_b64 s6, s[6:7]
	s_mov_b32 s100, s6
	s_atomic_add s100, s[4:5], 0x0 glc
